# layer-1 weight conversion: 588 of 1296 tile units moved into the idle last round of layer 0's second gate/up GEMM (workgroups 172-255), rest stays in layer 1's first norm phase
# speedup vs baseline: 1.0142x; 1.0069x over previous
; __device__ __forceinline__ void convert_layer(PP P, int l, LAS unsigned char* lds, const Ids I) {
;     ...
;     for (int u = BID; u < 7 * 176 + 64; u += NB) {
;         const int mi = u / 176, uu = u - mi * 176;
;         if (mi == 0)      conv_tile4(P->in[I_F1G] + wl, 1024, 2816, (bf16_t*)(ws + WS_WGU1), 5, uu, T, I);
;         else if (mi == 1) conv_tile4(P->in[I_F1U] + wl, 1024, 2816, (bf16_t*)(ws + WS_WGU1), 6, uu, T, I);
;         else if (mi == 2) conv_tile4(P->in[I_F1D] + wl, 2816, 1024, (bf16_t*)(ws + WS_WD1), 0, uu, T, I);
;         else if (mi == 3) conv_tile4(P->in[I_WIN] + wl, 1024, 2816, (bf16_t*)(ws + WS_WIN), 4, uu, T, I);
;         else if (mi == 4) conv_tile4(P->in[I_F2G] + wl, 1024, 2816, (bf16_t*)(ws + WS_WGU2), 5, uu, T, I);
;         else if (mi == 5) conv_tile4(P->in[I_F2U] + wl, 1024, 2816, (bf16_t*)(ws + WS_WGU2), 6, uu, T, I);
;         else if (mi == 6) conv_tile4(P->in[I_F2D] + wl, 2816, 1024, (bf16_t*)(ws + WS_WD2), 0, uu, T, I);
;         else              conv_tile4(P->in[I_WOUT] + (size_t)l * 1024 * 1024, 1024, 1024, (bf16_t*)(ws + WS_WOUT), 0, uu, T, I);
;     }
; __global__ void __launch_bounds__(512) mega(Params Pval) {
;     ...
;             } else if (sub == 1 || sub == 10) {
;                 EpiSwiGLU E{(bf16_t*)(ws + WS_R1)}; run_gemm(lds, (const bf16_t*)(ws + WS_HB), (const bf16_t*)(ws + (sub == 1 ? WS_WGU1 : WS_WGU2)), MT, 2 * FF, 1024, E, I);
.LBB0_412:
	v_readlane_b32 s30, v254, 45
	s_mov_b32 s25, s45
	v_readlane_b32 s27, v254, 47
	s_barrier
	s_cmp_eq_u32 s33, 12
	s_cbranch_scc0 .LBB0_413
	s_cmpk_lt_u32 s93, 0xac
	s_cbranch_scc1 .LBB0_413
	s_mov_b64 s[28:29], s[12:13]
	s_add_i32 s22, s93, 0xffffff54
	s_add_i32 s3, s93, 0xfffffb34
	s_movk_i32 s100, 0x54
	s_mov_b64 s[26:27], 0xb00000
	s_branch .LBB0_504
.Lcv_ret1:
	s_mov_b64 s[12:13], s[28:29]
	s_mov_b32 s25, s45
	v_readlane_b32 s27, v254, 47

; __device__ __forceinline__ void convert_layer(PP P, int l, LAS unsigned char* lds, const Ids I) {
;     ...
;     for (int u = BID; u < 7 * 176 + 64; u += NB) {
;         const int mi = u / 176, uu = u - mi * 176;
;         if (mi == 0)      conv_tile4(P->in[I_F1G] + wl, 1024, 2816, (bf16_t*)(ws + WS_WGU1), 5, uu, T, I);
;         else if (mi == 1) conv_tile4(P->in[I_F1U] + wl, 1024, 2816, (bf16_t*)(ws + WS_WGU1), 6, uu, T, I);
;         else if (mi == 2) conv_tile4(P->in[I_F1D] + wl, 2816, 1024, (bf16_t*)(ws + WS_WD1), 0, uu, T, I);
;         else if (mi == 3) conv_tile4(P->in[I_WIN] + wl, 1024, 2816, (bf16_t*)(ws + WS_WIN), 4, uu, T, I);
;         else if (mi == 4) conv_tile4(P->in[I_F2G] + wl, 1024, 2816, (bf16_t*)(ws + WS_WGU2), 5, uu, T, I);
;         else if (mi == 5) conv_tile4(P->in[I_F2U] + wl, 1024, 2816, (bf16_t*)(ws + WS_WGU2), 6, uu, T, I);
;         else if (mi == 6) conv_tile4(P->in[I_F2D] + wl, 2816, 1024, (bf16_t*)(ws + WS_WD2), 0, uu, T, I);
;         else              conv_tile4(P->in[I_WOUT] + (size_t)l * 1024 * 1024, 1024, 1024, (bf16_t*)(ws + WS_WOUT), 0, uu, T, I);
;     }
; __global__ void __launch_bounds__(512) mega(Params Pval) {
;     ...
;                 if (sub == 0 && l == 1) convert_layer(P, 1, lds, I);
.LBB0_500:
	s_and_b64 vcc, exec, s[0:1]
	s_cbranch_vccz .LBB0_591
	s_cmp_eq_u32 s30, 0
	s_cselect_b64 s[0:1], -1, 0
	s_cmp_eq_u32 s43, 1
	s_cselect_b64 s[4:5], -1, 0
	v_readlane_b32 s8, v254, 16
	s_and_b64 s[6:7], s[0:1], s[4:5]
	v_readlane_b32 s9, v254, 17
	s_and_b64 s[6:7], s[8:9], s[6:7]
	s_andn2_b64 vcc, exec, s[6:7]
	s_mov_b64 s[26:27], 0xb00000
	s_cbranch_vccnz .LBB0_532
	s_add_i32 s3, s93, 0xfffffe2c
	s_add_i32 s22, s93, 0x24c
	s_movk_i32 s100, 0x100
	s_branch .LBB0_504
.Lcv_exit:
	s_cmp_eq_u32 s33, 12
	s_cbranch_scc1 .Lcv_ret1
	s_branch .LBB0_532
.LBB0_503:
	s_add_i32 s22, s22, s100
	s_add_i32 s3, s3, s100
	s_movk_i32 s6, 0x510
	s_cmp_eq_u32 s33, 12
	s_cselect_b32 s6, 0x24c, s6
	s_cmp_lt_i32 s22, s6
	s_waitcnt lgkmcnt(0)
	s_cbranch_scc0 .Lcv_exit
